# q-projection rope epilogue pipelining depth 6 -> 8 (otherwise identical to the previous best)
# baseline (speedup 1.0000x reference)
; DI u16 f2bf(float x) { return (u16)(pack2(x, 0.f) & 0xffffu); }
; DI int crow(int i, int h) { return (i & 3) + 8 * (i >> 2) + 4 * h; }
; __global__ void __launch_bounds__(256, 2) fwd_megakernel(Params p) {
;     ...
;           if (is_rope) {
; #pragma unroll
;             for (int mt = 0; mt < 2; mt++)
; #pragma unroll
;               for (int i = 0; i < 16; i++) {
;                 const int m = m0 + wm * 64 + mt * 32 + crow(i, h);
;                 const float v0 = acc[mt][0][i], v1 = acc[mt][1][i];
;                 const int pos = tok_pos(m);
;                 const float c = ct[pos * 32 + r], s = st[pos * 32 + r];
;                 Q[(long)m * 1536 + nw0 + r] = f2bf((v0 * c - v1 * s) * QSCALE);
;                 Q[(long)m * 1536 + nw0 + 32 + r] = f2bf((v1 * c + v0 * s) * QSCALE);
;               }
.LBB0_567:
	s_andn2_saveexec_b64 s[52:53], s[0:1]
	s_cbranch_execz .LBB0_548
	v_cmp_gt_i32_e32 vcc, s33, v99
	v_or_b32_e32 v100, 0x400, v100
	s_nop 0
	v_cndmask_b32_e32 v100, v100, v99, vcc
	v_lshl_or_b32 v100, v100, 5, v69
	v_ashrrev_i32_e32 v101, 31, v100
	v_lshlrev_b64 v[100:101], 2, v[100:101]
	v_lshl_add_u64 v[102:103], s[34:35], 0, v[100:101]
	v_lshl_add_u64 v[100:101], s[36:37], 0, v[100:101]
	global_load_dword v228, v[102:103], off
	v_cmp_gt_i32_e32 vcc, s33, v98
	global_load_dword v229, v[100:101], off
	s_waitcnt vmcnt(0)
	v_mul_f32_e32 v100, v50, v229
	v_fma_f32 v100, v34, v228, -v100
	v_mul_f32_e32 v34, v34, v229
	v_mul_f32_e32 v100, 0x3dd53b94, v100
	v_fmac_f32_e32 v34, v50, v228
	v_cvt_pk_bf16_f32 v104, v100, s0
	v_mad_i64_i32 v[100:101], s[0:1], v99, s85, v[66:67]
	v_mul_f32_e32 v34, 0x3dd53b94, v34
	s_nop 0
	v_cvt_pk_bf16_f32 v34, v34, s0
	global_store_short v[100:101], v34, off offset:64
	v_and_or_b32 v34, v98, 5, v210
	v_cndmask_b32_e32 v34, v34, v98, vcc
	global_store_short v[100:101], v104, off
	v_lshl_or_b32 v100, v34, 5, v69
	v_ashrrev_i32_e32 v101, 31, v100
	v_lshlrev_b64 v[100:101], 2, v[100:101]
	v_lshl_add_u64 v[102:103], s[34:35], 0, v[100:101]
	v_lshl_add_u64 v[100:101], s[36:37], 0, v[100:101]
	global_load_dword v34, v[102:103], off
	global_load_dword v50, v[100:101], off
	v_cmp_gt_i32_e32 vcc, s33, v97
	s_waitcnt vmcnt(0)
	v_mul_f32_e32 v99, v51, v50
	v_fma_f32 v99, v35, v34, -v99
	v_mul_f32_e32 v35, v35, v50
	v_mul_f32_e32 v99, 0x3dd53b94, v99
	v_fmac_f32_e32 v35, v51, v34
	v_cvt_pk_bf16_f32 v100, v99, s0
	v_mad_i64_i32 v[98:99], s[0:1], v98, s85, v[66:67]
	v_mul_f32_e32 v34, 0x3dd53b94, v35
	s_nop 0
	v_cvt_pk_bf16_f32 v34, v34, s0
	global_store_short v[98:99], v34, off offset:64
	v_and_or_b32 v34, v97, 6, v210
	v_cndmask_b32_e32 v34, v34, v97, vcc
	v_lshl_or_b32 v34, v34, 5, v69
	v_ashrrev_i32_e32 v35, 31, v34
	v_lshlrev_b64 v[34:35], 2, v[34:35]
	v_lshl_add_u64 v[50:51], s[34:35], 0, v[34:35]
	v_lshl_add_u64 v[34:35], s[36:37], 0, v[34:35]
	global_load_dword v50, v[50:51], off
	v_cmp_gt_i32_e32 vcc, s33, v96
	global_load_dword v51, v[34:35], off
	s_waitcnt vmcnt(0)
	v_mul_f32_e32 v34, v52, v51
	v_fma_f32 v34, v36, v50, -v34
	v_mul_f32_e32 v36, v36, v51
	v_mul_f32_e32 v34, 0x3dd53b94, v34
	v_fmac_f32_e32 v36, v52, v50
	global_store_short v[98:99], v100, off
	v_cvt_pk_bf16_f32 v98, v34, s0
	v_mad_i64_i32 v[34:35], s[0:1], v97, s85, v[66:67]
	v_mul_f32_e32 v36, 0x3dd53b94, v36
	s_nop 0
	v_cvt_pk_bf16_f32 v36, v36, s0
	global_store_short v[34:35], v98, off
	global_store_short v[34:35], v36, off offset:64
	v_and_or_b32 v34, v96, 7, v210
	v_cndmask_b32_e32 v34, v34, v96, vcc
	v_lshl_or_b32 v34, v34, 5, v69
	v_ashrrev_i32_e32 v35, 31, v34
	v_lshlrev_b64 v[34:35], 2, v[34:35]
	v_lshl_add_u64 v[50:51], s[34:35], 0, v[34:35]
	v_lshl_add_u64 v[34:35], s[36:37], 0, v[34:35]
	global_load_dword v36, v[50:51], off
	v_cmp_gt_i32_e32 vcc, s33, v95
	global_load_dword v50, v[34:35], off
	s_waitcnt vmcnt(0)
	v_mul_f32_e32 v34, v53, v50
	v_fma_f32 v34, v37, v36, -v34
	v_mul_f32_e32 v37, v37, v50
	v_mul_f32_e32 v34, 0x3dd53b94, v34
	v_fmac_f32_e32 v37, v53, v36
	v_cvt_pk_bf16_f32 v51, v34, s0
	v_mad_i64_i32 v[34:35], s[0:1], v96, s85, v[66:67]
	v_mul_f32_e32 v36, 0x3dd53b94, v37
	s_nop 0
	v_cvt_pk_bf16_f32 v36, v36, s0
	global_store_short v[34:35], v51, off
	global_store_short v[34:35], v36, off offset:64
	v_and_or_b32 v34, v95, 12, v210
	v_cndmask_b32_e32 v34, v34, v95, vcc
	v_lshl_or_b32 v34, v34, 5, v69
	v_ashrrev_i32_e32 v35, 31, v34
	v_lshlrev_b64 v[34:35], 2, v[34:35]
	v_lshl_add_u64 v[36:37], s[34:35], 0, v[34:35]
	v_lshl_add_u64 v[34:35], s[36:37], 0, v[34:35]
	global_load_dword v234, v[36:37], off
	v_cmp_gt_i32_e32 vcc, s33, v94
	global_load_dword v235, v[34:35], off
	v_and_or_b32 v34, v94, 13, v210
	v_cndmask_b32_e32 v34, v34, v94, vcc
	v_lshl_or_b32 v34, v34, 5, v69
	v_ashrrev_i32_e32 v35, 31, v34
	v_lshlrev_b64 v[34:35], 2, v[34:35]
	v_lshl_add_u64 v[36:37], s[34:35], 0, v[34:35]
	v_lshl_add_u64 v[34:35], s[36:37], 0, v[34:35]
	global_load_dword v236, v[36:37], off
	v_cmp_gt_i32_e32 vcc, s33, v93
	global_load_dword v237, v[34:35], off
	v_and_or_b32 v34, v93, 14, v210
	v_cndmask_b32_e32 v34, v34, v93, vcc
	v_lshl_or_b32 v34, v34, 5, v69
	v_ashrrev_i32_e32 v35, 31, v34
	v_lshlrev_b64 v[34:35], 2, v[34:35]
	v_lshl_add_u64 v[36:37], s[34:35], 0, v[34:35]
	v_lshl_add_u64 v[34:35], s[36:37], 0, v[34:35]
	global_load_dword v238, v[36:37], off
	v_cmp_gt_i32_e32 vcc, s33, v92
	global_load_dword v239, v[34:35], off
	v_and_or_b32 v34, v92, 15, v210
	v_cndmask_b32_e32 v34, v34, v92, vcc
	v_lshl_or_b32 v34, v34, 5, v69
	v_ashrrev_i32_e32 v35, 31, v34
	v_lshlrev_b64 v[34:35], 2, v[34:35]
	v_lshl_add_u64 v[36:37], s[34:35], 0, v[34:35]
	v_lshl_add_u64 v[34:35], s[36:37], 0, v[34:35]
	global_load_dword v240, v[36:37], off
	v_cmp_gt_i32_e32 vcc, s33, v91
	global_load_dword v241, v[34:35], off
	v_and_or_b32 v34, v91, 20, v210
	v_cndmask_b32_e32 v34, v34, v91, vcc
	v_lshl_or_b32 v34, v34, 5, v69
	v_ashrrev_i32_e32 v35, 31, v34
	v_lshlrev_b64 v[34:35], 2, v[34:35]
	v_lshl_add_u64 v[36:37], s[34:35], 0, v[34:35]
	v_lshl_add_u64 v[34:35], s[36:37], 0, v[34:35]
	global_load_dword v242, v[36:37], off
	v_cmp_gt_i32_e32 vcc, s33, v90
	global_load_dword v243, v[34:35], off
	v_and_or_b32 v34, v90, 21, v210
	v_cndmask_b32_e32 v34, v34, v90, vcc
	v_lshl_or_b32 v34, v34, 5, v69
	v_ashrrev_i32_e32 v35, 31, v34
	v_lshlrev_b64 v[34:35], 2, v[34:35]
	v_lshl_add_u64 v[36:37], s[34:35], 0, v[34:35]
	v_lshl_add_u64 v[34:35], s[36:37], 0, v[34:35]
	global_load_dword v228, v[36:37], off
	v_cmp_gt_i32_e32 vcc, s33, v89
	global_load_dword v229, v[34:35], off
	v_and_or_b32 v34, v89, 22, v210
	v_cndmask_b32_e32 v34, v34, v89, vcc
	v_lshl_or_b32 v34, v34, 5, v69
	v_ashrrev_i32_e32 v35, 31, v34
	v_lshlrev_b64 v[34:35], 2, v[34:35]
	v_lshl_add_u64 v[36:37], s[34:35], 0, v[34:35]
	v_lshl_add_u64 v[34:35], s[36:37], 0, v[34:35]
	global_load_dword v230, v[36:37], off
	v_cmp_gt_i32_e32 vcc, s33, v88
	global_load_dword v231, v[34:35], off
	v_and_or_b32 v34, v88, 23, v210
	v_cndmask_b32_e32 v34, v34, v88, vcc
	v_lshl_or_b32 v34, v34, 5, v69
	v_ashrrev_i32_e32 v35, 31, v34
	v_lshlrev_b64 v[34:35], 2, v[34:35]
	v_lshl_add_u64 v[36:37], s[34:35], 0, v[34:35]
	v_lshl_add_u64 v[34:35], s[36:37], 0, v[34:35]
	global_load_dword v232, v[36:37], off
	v_cmp_gt_i32_e32 vcc, s33, v87
	global_load_dword v233, v[34:35], off
	s_waitcnt vmcnt(14)
; DI u16 f2bf(float x) { return (u16)(pack2(x, 0.f) & 0xffffu); }
; DI int crow(int i, int h) { return (i & 3) + 8 * (i >> 2) + 4 * h; }
; __global__ void __launch_bounds__(256, 2) fwd_megakernel(Params p) {
;     ...
;           if (is_rope) {
; #pragma unroll
;             for (int mt = 0; mt < 2; mt++)
; #pragma unroll
;               for (int i = 0; i < 16; i++) {
;                 const int m = m0 + wm * 64 + mt * 32 + crow(i, h);
;                 const float v0 = acc[mt][0][i], v1 = acc[mt][1][i];
;                 const int pos = tok_pos(m);
;                 const float c = ct[pos * 32 + r], s = st[pos * 32 + r];
;                 Q[(long)m * 1536 + nw0 + r] = f2bf((v0 * c - v1 * s) * QSCALE);
;                 Q[(long)m * 1536 + nw0 + 32 + r] = f2bf((v1 * c + v0 * s) * QSCALE);
;               }
	v_mul_f32_e32 v34, v54, v235
	v_fma_f32 v34, v38, v234, -v34
	v_mul_f32_e32 v37, v38, v235
	v_mul_f32_e32 v34, 0x3dd53b94, v34
	v_fmac_f32_e32 v37, v54, v234
	v_cvt_pk_bf16_f32 v50, v34, s0
	v_mad_i64_i32 v[34:35], s[0:1], v95, s85, v[66:67]
	v_mul_f32_e32 v36, 0x3dd53b94, v37
	s_nop 0
	v_cvt_pk_bf16_f32 v36, v36, s0
	global_store_short v[34:35], v50, off
	global_store_short v[34:35], v36, off offset:64
	v_and_or_b32 v34, v87, 28, v210
	v_cndmask_b32_e32 v34, v34, v87, vcc
	v_lshl_or_b32 v34, v34, 5, v69
	v_ashrrev_i32_e32 v35, 31, v34
	v_lshlrev_b64 v[34:35], 2, v[34:35]
	v_lshl_add_u64 v[36:37], s[34:35], 0, v[34:35]
	v_lshl_add_u64 v[34:35], s[36:37], 0, v[34:35]
	global_load_dword v234, v[36:37], off
	v_cmp_gt_i32_e32 vcc, s33, v86
	global_load_dword v235, v[34:35], off
	s_waitcnt vmcnt(16)
	v_mul_f32_e32 v34, v55, v237
	v_fma_f32 v34, v39, v236, -v34
	v_mul_f32_e32 v37, v39, v237
	v_mul_f32_e32 v34, 0x3dd53b94, v34
	v_fmac_f32_e32 v37, v55, v236
	v_cvt_pk_bf16_f32 v38, v34, s0
	v_mad_i64_i32 v[34:35], s[0:1], v94, s85, v[66:67]
	v_mul_f32_e32 v36, 0x3dd53b94, v37
	s_nop 0
	v_cvt_pk_bf16_f32 v36, v36, s0
	global_store_short v[34:35], v38, off
	global_store_short v[34:35], v36, off offset:64
	v_and_or_b32 v34, v86, 29, v210
	v_cndmask_b32_e32 v34, v34, v86, vcc
	v_lshl_or_b32 v34, v34, 5, v69
	v_ashrrev_i32_e32 v35, 31, v34
	v_lshlrev_b64 v[34:35], 2, v[34:35]
	v_lshl_add_u64 v[36:37], s[34:35], 0, v[34:35]
	v_lshl_add_u64 v[34:35], s[36:37], 0, v[34:35]
	global_load_dword v236, v[36:37], off
	v_cmp_gt_i32_e32 vcc, s33, v85
	global_load_dword v237, v[34:35], off
	s_waitcnt vmcnt(18)
	v_mul_f32_e32 v34, v56, v239
	v_fma_f32 v34, v40, v238, -v34
	v_mul_f32_e32 v37, v40, v239
	v_mul_f32_e32 v34, 0x3dd53b94, v34
	v_fmac_f32_e32 v37, v56, v238
	v_cvt_pk_bf16_f32 v38, v34, s0
	v_mad_i64_i32 v[34:35], s[0:1], v93, s85, v[66:67]
	v_mul_f32_e32 v36, 0x3dd53b94, v37
	s_nop 0
	v_cvt_pk_bf16_f32 v36, v36, s0
	global_store_short v[34:35], v38, off
	global_store_short v[34:35], v36, off offset:64
	v_and_or_b32 v34, v85, 30, v210
	v_cndmask_b32_e32 v34, v34, v85, vcc
	v_lshl_or_b32 v34, v34, 5, v69
	v_ashrrev_i32_e32 v35, 31, v34
	v_lshlrev_b64 v[34:35], 2, v[34:35]
	v_lshl_add_u64 v[36:37], s[34:35], 0, v[34:35]
	v_lshl_add_u64 v[34:35], s[36:37], 0, v[34:35]
	global_load_dword v238, v[36:37], off
	v_cmp_gt_i32_e32 vcc, s33, v84
	global_load_dword v239, v[34:35], off
	s_waitcnt vmcnt(20)
	v_mul_f32_e32 v34, v57, v241
	v_fma_f32 v34, v41, v240, -v34
	v_mul_f32_e32 v37, v41, v241
	v_mul_f32_e32 v34, 0x3dd53b94, v34
	v_fmac_f32_e32 v37, v57, v240
	v_cvt_pk_bf16_f32 v38, v34, s0
	v_mad_i64_i32 v[34:35], s[0:1], v92, s85, v[66:67]
	v_mul_f32_e32 v36, 0x3dd53b94, v37
	s_nop 0
	v_cvt_pk_bf16_f32 v36, v36, s0
	global_store_short v[34:35], v38, off
	global_store_short v[34:35], v36, off offset:64
	v_and_or_b32 v34, v84, 31, v210
	v_cndmask_b32_e32 v34, v34, v84, vcc
	v_lshl_or_b32 v34, v34, 5, v69
	v_ashrrev_i32_e32 v35, 31, v34
	v_lshlrev_b64 v[34:35], 2, v[34:35]
	v_lshl_add_u64 v[36:37], s[34:35], 0, v[34:35]
	v_lshl_add_u64 v[34:35], s[36:37], 0, v[34:35]
	global_load_dword v240, v[36:37], off
	v_cmp_gt_i32_e32 vcc, s33, v83
	global_load_dword v241, v[34:35], off
	s_waitcnt vmcnt(22)
	v_mul_f32_e32 v34, v58, v243
	v_fma_f32 v34, v42, v242, -v34
	v_mul_f32_e32 v37, v42, v243
	v_mul_f32_e32 v34, 0x3dd53b94, v34
	v_fmac_f32_e32 v37, v58, v242
	v_cvt_pk_bf16_f32 v38, v34, s0
	v_mad_i64_i32 v[34:35], s[0:1], v91, s85, v[66:67]
	v_mul_f32_e32 v36, 0x3dd53b94, v37
	s_nop 0
	v_cvt_pk_bf16_f32 v36, v36, s0
	global_store_short v[34:35], v38, off
	global_store_short v[34:35], v36, off offset:64
	v_and_or_b32 v34, v83, 36, v210
	v_cndmask_b32_e32 v34, v34, v83, vcc
	v_lshl_or_b32 v34, v34, 5, v69
	v_ashrrev_i32_e32 v35, 31, v34
	v_lshlrev_b64 v[34:35], 2, v[34:35]
	v_lshl_add_u64 v[36:37], s[34:35], 0, v[34:35]
	v_lshl_add_u64 v[34:35], s[36:37], 0, v[34:35]
	global_load_dword v242, v[36:37], off
	v_cmp_gt_i32_e32 vcc, s33, v82
	global_load_dword v243, v[34:35], off
	s_waitcnt vmcnt(24)
	v_mul_f32_e32 v34, v59, v229
	v_fma_f32 v34, v43, v228, -v34
	v_mul_f32_e32 v37, v43, v229
	v_mul_f32_e32 v34, 0x3dd53b94, v34
	v_fmac_f32_e32 v37, v59, v228
	v_cvt_pk_bf16_f32 v38, v34, s0
	v_mad_i64_i32 v[34:35], s[0:1], v90, s85, v[66:67]
	v_mul_f32_e32 v36, 0x3dd53b94, v37
	s_nop 0
	v_cvt_pk_bf16_f32 v36, v36, s0
	global_store_short v[34:35], v38, off
	global_store_short v[34:35], v36, off offset:64
	s_waitcnt vmcnt(24)
	v_mul_f32_e32 v34, v60, v231
	v_fma_f32 v34, v44, v230, -v34
	v_mul_f32_e32 v37, v44, v231
	v_mul_f32_e32 v34, 0x3dd53b94, v34
	v_fmac_f32_e32 v37, v60, v230
	v_cvt_pk_bf16_f32 v38, v34, s0
	v_mad_i64_i32 v[34:35], s[0:1], v89, s85, v[66:67]
	v_mul_f32_e32 v36, 0x3dd53b94, v37
	s_nop 0
	v_cvt_pk_bf16_f32 v36, v36, s0
	global_store_short v[34:35], v38, off
	global_store_short v[34:35], v36, off offset:64
	s_waitcnt vmcnt(24)
	v_mul_f32_e32 v34, v61, v233
	v_fma_f32 v34, v45, v232, -v34
	v_mul_f32_e32 v37, v45, v233
	v_mul_f32_e32 v34, 0x3dd53b94, v34
	v_fmac_f32_e32 v37, v61, v232
	v_cvt_pk_bf16_f32 v38, v34, s0
	v_mad_i64_i32 v[34:35], s[0:1], v88, s85, v[66:67]
	v_mul_f32_e32 v36, 0x3dd53b94, v37
	s_nop 0
	v_cvt_pk_bf16_f32 v36, v36, s0
	global_store_short v[34:35], v38, off
	global_store_short v[34:35], v36, off offset:64
	s_waitcnt vmcnt(22)
	v_mul_f32_e32 v34, v62, v235
	v_fma_f32 v34, v46, v234, -v34
	v_mul_f32_e32 v37, v46, v235
	v_mul_f32_e32 v34, 0x3dd53b94, v34
	v_fmac_f32_e32 v37, v62, v234
	v_cvt_pk_bf16_f32 v38, v34, s0
	v_mad_i64_i32 v[34:35], s[0:1], v87, s85, v[66:67]
	v_mul_f32_e32 v36, 0x3dd53b94, v37
	s_nop 0
	v_cvt_pk_bf16_f32 v36, v36, s0
	global_store_short v[34:35], v38, off
	global_store_short v[34:35], v36, off offset:64
	s_waitcnt vmcnt(20)
; DI u16 f2bf(float x) { return (u16)(pack2(x, 0.f) & 0xffffu); }
; DI int crow(int i, int h) { return (i & 3) + 8 * (i >> 2) + 4 * h; }
; __global__ void __launch_bounds__(256, 2) fwd_megakernel(Params p) {
;     ...
;           if (is_rope) {
; #pragma unroll
;             for (int mt = 0; mt < 2; mt++)
; #pragma unroll
;               for (int i = 0; i < 16; i++) {
;                 const int m = m0 + wm * 64 + mt * 32 + crow(i, h);
;                 const float v0 = acc[mt][0][i], v1 = acc[mt][1][i];
;                 const int pos = tok_pos(m);
;                 const float c = ct[pos * 32 + r], s = st[pos * 32 + r];
;                 Q[(long)m * 1536 + nw0 + r] = f2bf((v0 * c - v1 * s) * QSCALE);
;                 Q[(long)m * 1536 + nw0 + 32 + r] = f2bf((v1 * c + v0 * s) * QSCALE);
;               }
	v_mul_f32_e32 v34, v63, v237
	v_fma_f32 v34, v47, v236, -v34
	v_mul_f32_e32 v37, v47, v237
	v_mul_f32_e32 v34, 0x3dd53b94, v34
	v_fmac_f32_e32 v37, v63, v236
	v_cvt_pk_bf16_f32 v38, v34, s0
	v_mad_i64_i32 v[34:35], s[0:1], v86, s85, v[66:67]
	v_mul_f32_e32 v36, 0x3dd53b94, v37
	s_nop 0
	v_cvt_pk_bf16_f32 v36, v36, s0
	global_store_short v[34:35], v38, off
	global_store_short v[34:35], v36, off offset:64
	s_waitcnt vmcnt(18)
	v_mul_f32_e32 v34, v64, v239
	v_fma_f32 v34, v48, v238, -v34
	v_mul_f32_e32 v37, v48, v239
	v_mul_f32_e32 v34, 0x3dd53b94, v34
	v_fmac_f32_e32 v37, v64, v238
	v_cvt_pk_bf16_f32 v38, v34, s0
	v_mad_i64_i32 v[34:35], s[0:1], v85, s85, v[66:67]
	v_mul_f32_e32 v36, 0x3dd53b94, v37
	s_nop 0
	v_cvt_pk_bf16_f32 v36, v36, s0
	global_store_short v[34:35], v38, off
	global_store_short v[34:35], v36, off offset:64
	s_waitcnt vmcnt(16)
	v_mul_f32_e32 v34, v65, v241
	v_fma_f32 v34, v49, v240, -v34
	v_mul_f32_e32 v37, v49, v241
	v_mul_f32_e32 v34, 0x3dd53b94, v34
	v_fmac_f32_e32 v37, v65, v240
	v_cvt_pk_bf16_f32 v38, v34, s0
	v_mad_i64_i32 v[34:35], s[0:1], v84, s85, v[66:67]
	v_mul_f32_e32 v36, 0x3dd53b94, v37
	s_nop 0
	v_cvt_pk_bf16_f32 v36, v36, s0
	global_store_short v[34:35], v38, off
	global_store_short v[34:35], v36, off offset:64
	s_waitcnt vmcnt(14)
	v_mul_f32_e32 v34, v2, v243
	v_fma_f32 v34, v18, v242, -v34
	v_mul_f32_e32 v18, v18, v243
	v_mul_f32_e32 v34, 0x3dd53b94, v34
	v_fmac_f32_e32 v18, v2, v242
	v_cvt_pk_bf16_f32 v38, v34, s0
	v_mad_i64_i32 v[34:35], s[0:1], v83, s85, v[66:67]
	v_mul_f32_e32 v2, 0x3dd53b94, v18
	s_nop 0
	v_cvt_pk_bf16_f32 v2, v2, s0
	global_store_short v[34:35], v2, off offset:64
	v_and_or_b32 v2, v82, 37, v210
	v_cndmask_b32_e32 v2, v2, v82, vcc
	global_store_short v[34:35], v38, off
	v_lshl_or_b32 v34, v2, 5, v69
	v_ashrrev_i32_e32 v35, 31, v34
	v_lshlrev_b64 v[34:35], 2, v[34:35]
	v_lshl_add_u64 v[36:37], s[34:35], 0, v[34:35]
	v_lshl_add_u64 v[34:35], s[36:37], 0, v[34:35]
	global_load_dword v2, v[36:37], off
	global_load_dword v18, v[34:35], off
	v_cmp_gt_i32_e32 vcc, s33, v81
	s_waitcnt vmcnt(0)
	v_mul_f32_e32 v34, v3, v18
	v_fma_f32 v34, v19, v2, -v34
	v_mul_f32_e32 v18, v19, v18
	v_mul_f32_e32 v34, 0x3dd53b94, v34
	v_fmac_f32_e32 v18, v3, v2
	v_cvt_pk_bf16_f32 v36, v34, s0
	v_mad_i64_i32 v[34:35], s[0:1], v82, s85, v[66:67]
	v_mul_f32_e32 v2, 0x3dd53b94, v18
	s_nop 0
	v_cvt_pk_bf16_f32 v2, v2, s0
	global_store_short v[34:35], v2, off offset:64
	v_and_or_b32 v2, v81, 38, v210
	v_cndmask_b32_e32 v2, v2, v81, vcc
	v_lshl_or_b32 v2, v2, 5, v69
	v_ashrrev_i32_e32 v3, 31, v2
	v_lshlrev_b64 v[2:3], 2, v[2:3]
	v_lshl_add_u64 v[18:19], s[34:35], 0, v[2:3]
	v_lshl_add_u64 v[2:3], s[36:37], 0, v[2:3]
	global_load_dword v18, v[18:19], off
	v_cmp_gt_i32_e32 vcc, s33, v80
	global_load_dword v19, v[2:3], off
	s_waitcnt vmcnt(0)
	v_mul_f32_e32 v2, v4, v19
	v_fma_f32 v2, v20, v18, -v2
	v_mul_f32_e32 v19, v20, v19
	v_mul_f32_e32 v2, 0x3dd53b94, v2
	v_fmac_f32_e32 v19, v4, v18
	global_store_short v[34:35], v36, off
	v_cvt_pk_bf16_f32 v34, v2, s0
	v_mad_i64_i32 v[2:3], s[0:1], v81, s85, v[66:67]
	v_mul_f32_e32 v4, 0x3dd53b94, v19
	s_nop 0
	v_cvt_pk_bf16_f32 v4, v4, s0
	global_store_short v[2:3], v34, off
	global_store_short v[2:3], v4, off offset:64
	v_and_or_b32 v2, v80, 39, v210
	v_cndmask_b32_e32 v2, v2, v80, vcc
	v_lshl_or_b32 v2, v2, 5, v69
	v_ashrrev_i32_e32 v3, 31, v2
	v_lshlrev_b64 v[2:3], 2, v[2:3]
	v_lshl_add_u64 v[18:19], s[34:35], 0, v[2:3]
	v_lshl_add_u64 v[2:3], s[36:37], 0, v[2:3]
	global_load_dword v4, v[18:19], off
	v_cmp_gt_i32_e32 vcc, s33, v79
	global_load_dword v18, v[2:3], off
	s_waitcnt vmcnt(0)
	v_mul_f32_e32 v2, v5, v18
	v_fma_f32 v2, v21, v4, -v2
	v_mul_f32_e32 v18, v21, v18
	v_mul_f32_e32 v2, 0x3dd53b94, v2
	v_fmac_f32_e32 v18, v5, v4
	v_cvt_pk_bf16_f32 v19, v2, s0
	v_mad_i64_i32 v[2:3], s[0:1], v80, s85, v[66:67]
	v_mul_f32_e32 v4, 0x3dd53b94, v18
	s_nop 0
	v_cvt_pk_bf16_f32 v4, v4, s0
	global_store_short v[2:3], v19, off
	global_store_short v[2:3], v4, off offset:64
	v_and_or_b32 v2, v79, 44, v210
	v_cndmask_b32_e32 v2, v2, v79, vcc
	v_lshl_or_b32 v2, v2, 5, v69
	v_ashrrev_i32_e32 v3, 31, v2
	v_lshlrev_b64 v[2:3], 2, v[2:3]
	v_lshl_add_u64 v[4:5], s[34:35], 0, v[2:3]
	v_lshl_add_u64 v[2:3], s[36:37], 0, v[2:3]
	global_load_dword v232, v[4:5], off
	v_cmp_gt_i32_e32 vcc, s33, v78
	global_load_dword v233, v[2:3], off
	v_and_or_b32 v2, v78, 45, v210
	v_cndmask_b32_e32 v2, v2, v78, vcc
	v_lshl_or_b32 v2, v2, 5, v69
	v_ashrrev_i32_e32 v3, 31, v2
	v_lshlrev_b64 v[2:3], 2, v[2:3]
	v_lshl_add_u64 v[4:5], s[34:35], 0, v[2:3]
	v_lshl_add_u64 v[2:3], s[36:37], 0, v[2:3]
	global_load_dword v234, v[4:5], off
	v_cmp_gt_i32_e32 vcc, s33, v77
	global_load_dword v235, v[2:3], off
	v_and_or_b32 v2, v77, 46, v210
	v_cndmask_b32_e32 v2, v2, v77, vcc
	v_lshl_or_b32 v2, v2, 5, v69
	v_ashrrev_i32_e32 v3, 31, v2
	v_lshlrev_b64 v[2:3], 2, v[2:3]
	v_lshl_add_u64 v[4:5], s[34:35], 0, v[2:3]
	v_lshl_add_u64 v[2:3], s[36:37], 0, v[2:3]
	global_load_dword v236, v[4:5], off
	v_cmp_gt_i32_e32 vcc, s33, v76
	global_load_dword v237, v[2:3], off
	v_and_or_b32 v2, v76, 47, v210
	v_cndmask_b32_e32 v2, v2, v76, vcc
	v_lshl_or_b32 v2, v2, 5, v69
	v_ashrrev_i32_e32 v3, 31, v2
	v_lshlrev_b64 v[2:3], 2, v[2:3]
	v_lshl_add_u64 v[4:5], s[34:35], 0, v[2:3]
	v_lshl_add_u64 v[2:3], s[36:37], 0, v[2:3]
	global_load_dword v238, v[4:5], off
	v_cmp_gt_i32_e32 vcc, s33, v75
	global_load_dword v239, v[2:3], off
	v_and_or_b32 v2, v75, 52, v210
	v_cndmask_b32_e32 v2, v2, v75, vcc
	v_lshl_or_b32 v2, v2, 5, v69
	v_ashrrev_i32_e32 v3, 31, v2
	v_lshlrev_b64 v[2:3], 2, v[2:3]
	v_lshl_add_u64 v[4:5], s[34:35], 0, v[2:3]
	v_lshl_add_u64 v[2:3], s[36:37], 0, v[2:3]
	global_load_dword v240, v[4:5], off
	v_cmp_gt_i32_e32 vcc, s33, v74
	global_load_dword v241, v[2:3], off
	v_and_or_b32 v2, v74, 53, v210
	v_cndmask_b32_e32 v2, v2, v74, vcc
	v_lshl_or_b32 v2, v2, 5, v69
	v_ashrrev_i32_e32 v3, 31, v2
	v_lshlrev_b64 v[2:3], 2, v[2:3]
	v_lshl_add_u64 v[4:5], s[34:35], 0, v[2:3]
	v_lshl_add_u64 v[2:3], s[36:37], 0, v[2:3]
	global_load_dword v242, v[4:5], off
	v_cmp_gt_i32_e32 vcc, s33, v73
	global_load_dword v243, v[2:3], off
	v_and_or_b32 v2, v73, 54, v210
	v_cndmask_b32_e32 v2, v2, v73, vcc
	v_lshl_or_b32 v2, v2, 5, v69
	v_ashrrev_i32_e32 v3, 31, v2
	v_lshlrev_b64 v[2:3], 2, v[2:3]
	v_lshl_add_u64 v[4:5], s[34:35], 0, v[2:3]
	v_lshl_add_u64 v[2:3], s[36:37], 0, v[2:3]
	global_load_dword v228, v[4:5], off
	v_cmp_gt_i32_e32 vcc, s33, v72
	global_load_dword v229, v[2:3], off
	v_and_or_b32 v2, v72, 55, v210
	v_cndmask_b32_e32 v2, v2, v72, vcc
	v_lshl_or_b32 v2, v2, 5, v69
	v_ashrrev_i32_e32 v3, 31, v2
	v_lshlrev_b64 v[2:3], 2, v[2:3]
	v_lshl_add_u64 v[4:5], s[34:35], 0, v[2:3]
	v_lshl_add_u64 v[2:3], s[36:37], 0, v[2:3]
	global_load_dword v230, v[4:5], off
	v_cmp_gt_i32_e32 vcc, s33, v71
	global_load_dword v231, v[2:3], off
	s_waitcnt vmcnt(14)
; DI u16 f2bf(float x) { return (u16)(pack2(x, 0.f) & 0xffffu); }
; DI int crow(int i, int h) { return (i & 3) + 8 * (i >> 2) + 4 * h; }
; __global__ void __launch_bounds__(256, 2) fwd_megakernel(Params p) {
;     ...
;           if (is_rope) {
; #pragma unroll
;             for (int mt = 0; mt < 2; mt++)
; #pragma unroll
;               for (int i = 0; i < 16; i++) {
;                 const int m = m0 + wm * 64 + mt * 32 + crow(i, h);
;                 const float v0 = acc[mt][0][i], v1 = acc[mt][1][i];
;                 const int pos = tok_pos(m);
;                 const float c = ct[pos * 32 + r], s = st[pos * 32 + r];
;                 Q[(long)m * 1536 + nw0 + r] = f2bf((v0 * c - v1 * s) * QSCALE);
;                 Q[(long)m * 1536 + nw0 + 32 + r] = f2bf((v1 * c + v0 * s) * QSCALE);
;               }
	v_mul_f32_e32 v2, v6, v233
	v_fma_f32 v2, v22, v232, -v2
	v_mul_f32_e32 v5, v22, v233
	v_mul_f32_e32 v2, 0x3dd53b94, v2
	v_fmac_f32_e32 v5, v6, v232
	v_cvt_pk_bf16_f32 v18, v2, s0
	v_mad_i64_i32 v[2:3], s[0:1], v79, s85, v[66:67]
	v_mul_f32_e32 v4, 0x3dd53b94, v5
	s_nop 0
	v_cvt_pk_bf16_f32 v4, v4, s0
	global_store_short v[2:3], v18, off
	global_store_short v[2:3], v4, off offset:64
	v_and_or_b32 v2, v71, 60, v210
	v_cndmask_b32_e32 v2, v2, v71, vcc
	v_lshl_or_b32 v2, v2, 5, v69
	v_ashrrev_i32_e32 v3, 31, v2
	v_lshlrev_b64 v[2:3], 2, v[2:3]
	v_lshl_add_u64 v[4:5], s[34:35], 0, v[2:3]
	v_lshl_add_u64 v[2:3], s[36:37], 0, v[2:3]
	global_load_dword v232, v[4:5], off
	v_cmp_gt_i32_e32 vcc, s33, v70
	global_load_dword v233, v[2:3], off
	s_waitcnt vmcnt(16)
	v_mul_f32_e32 v2, v7, v235
	v_fma_f32 v2, v23, v234, -v2
	v_mul_f32_e32 v5, v23, v235
	v_mul_f32_e32 v2, 0x3dd53b94, v2
	v_fmac_f32_e32 v5, v7, v234
	v_cvt_pk_bf16_f32 v6, v2, s0
	v_mad_i64_i32 v[2:3], s[0:1], v78, s85, v[66:67]
	v_mul_f32_e32 v4, 0x3dd53b94, v5
	s_nop 0
	v_cvt_pk_bf16_f32 v4, v4, s0
	global_store_short v[2:3], v6, off
	global_store_short v[2:3], v4, off offset:64
	v_and_or_b32 v2, v70, 61, v210
	v_cndmask_b32_e32 v2, v2, v70, vcc
	v_lshl_or_b32 v2, v2, 5, v69
	v_ashrrev_i32_e32 v3, 31, v2
	v_lshlrev_b64 v[2:3], 2, v[2:3]
	v_lshl_add_u64 v[4:5], s[34:35], 0, v[2:3]
	v_lshl_add_u64 v[2:3], s[36:37], 0, v[2:3]
	global_load_dword v234, v[4:5], off
	v_cmp_gt_i32_e32 vcc, s33, v68
	global_load_dword v235, v[2:3], off
	s_waitcnt vmcnt(18)
	v_mul_f32_e32 v2, v8, v237
	v_fma_f32 v2, v24, v236, -v2
	v_mul_f32_e32 v5, v24, v237
	v_mul_f32_e32 v2, 0x3dd53b94, v2
	v_fmac_f32_e32 v5, v8, v236
	v_cvt_pk_bf16_f32 v6, v2, s0
	v_mad_i64_i32 v[2:3], s[0:1], v77, s85, v[66:67]
	v_mul_f32_e32 v4, 0x3dd53b94, v5
	s_nop 0
	v_cvt_pk_bf16_f32 v4, v4, s0
	global_store_short v[2:3], v6, off
	global_store_short v[2:3], v4, off offset:64
	v_and_or_b32 v2, v68, 62, v210
	v_cndmask_b32_e32 v2, v2, v68, vcc
	v_lshl_or_b32 v2, v2, 5, v69
	v_ashrrev_i32_e32 v3, 31, v2
	v_lshlrev_b64 v[2:3], 2, v[2:3]
	v_lshl_add_u64 v[4:5], s[34:35], 0, v[2:3]
	v_lshl_add_u64 v[2:3], s[36:37], 0, v[2:3]
	global_load_dword v236, v[4:5], off
	v_cmp_gt_i32_e32 vcc, s33, v0
	global_load_dword v237, v[2:3], off
	s_waitcnt vmcnt(20)
	v_mul_f32_e32 v2, v9, v239
	v_fma_f32 v2, v25, v238, -v2
	v_mul_f32_e32 v5, v25, v239
	v_mul_f32_e32 v2, 0x3dd53b94, v2
	v_fmac_f32_e32 v5, v9, v238
	v_cvt_pk_bf16_f32 v6, v2, s0
	v_mad_i64_i32 v[2:3], s[0:1], v76, s85, v[66:67]
	v_mul_f32_e32 v4, 0x3dd53b94, v5
	s_nop 0
	v_cvt_pk_bf16_f32 v4, v4, s0
	global_store_short v[2:3], v6, off
	global_store_short v[2:3], v4, off offset:64
	v_and_or_b32 v2, v0, 63, v210
	v_cndmask_b32_e32 v2, v2, v0, vcc
	v_lshl_or_b32 v2, v2, 5, v69
	v_ashrrev_i32_e32 v3, 31, v2
	v_lshlrev_b64 v[2:3], 2, v[2:3]
	v_lshl_add_u64 v[4:5], s[34:35], 0, v[2:3]
	v_lshl_add_u64 v[2:3], s[36:37], 0, v[2:3]
	global_load_dword v238, v[4:5], off
	s_nop 0
	global_load_dword v239, v[2:3], off
	s_waitcnt vmcnt(22)
	v_mul_f32_e32 v2, v10, v241
	v_fma_f32 v2, v26, v240, -v2
	v_mul_f32_e32 v5, v26, v241
	v_mul_f32_e32 v2, 0x3dd53b94, v2
	v_fmac_f32_e32 v5, v10, v240
	v_cvt_pk_bf16_f32 v6, v2, s0
	v_mad_i64_i32 v[2:3], s[0:1], v75, s85, v[66:67]
	v_mul_f32_e32 v4, 0x3dd53b94, v5
	s_nop 0
	v_cvt_pk_bf16_f32 v4, v4, s0
	global_store_short v[2:3], v6, off
	global_store_short v[2:3], v4, off offset:64
	s_waitcnt vmcnt(22)
	v_mul_f32_e32 v2, v11, v243
	v_fma_f32 v2, v27, v242, -v2
	v_mul_f32_e32 v5, v27, v243
	v_mul_f32_e32 v2, 0x3dd53b94, v2
	v_fmac_f32_e32 v5, v11, v242
	v_cvt_pk_bf16_f32 v6, v2, s0
	v_mad_i64_i32 v[2:3], s[0:1], v74, s85, v[66:67]
	v_mul_f32_e32 v4, 0x3dd53b94, v5
	s_nop 0
	v_cvt_pk_bf16_f32 v4, v4, s0
	global_store_short v[2:3], v6, off
	global_store_short v[2:3], v4, off offset:64
	s_waitcnt vmcnt(22)
	v_mul_f32_e32 v2, v12, v229
	v_fma_f32 v2, v28, v228, -v2
	v_mul_f32_e32 v5, v28, v229
	v_mul_f32_e32 v2, 0x3dd53b94, v2
	v_fmac_f32_e32 v5, v12, v228
	v_cvt_pk_bf16_f32 v6, v2, s0
	v_mad_i64_i32 v[2:3], s[0:1], v73, s85, v[66:67]
	v_mul_f32_e32 v4, 0x3dd53b94, v5
	s_nop 0
	v_cvt_pk_bf16_f32 v4, v4, s0
	global_store_short v[2:3], v6, off
	global_store_short v[2:3], v4, off offset:64
	s_waitcnt vmcnt(22)
	v_mul_f32_e32 v2, v13, v231
	v_fma_f32 v2, v29, v230, -v2
	v_mul_f32_e32 v5, v29, v231
	v_mul_f32_e32 v2, 0x3dd53b94, v2
	v_fmac_f32_e32 v5, v13, v230
	v_cvt_pk_bf16_f32 v6, v2, s0
	v_mad_i64_i32 v[2:3], s[0:1], v72, s85, v[66:67]
	v_mul_f32_e32 v4, 0x3dd53b94, v5
	s_nop 0
	v_cvt_pk_bf16_f32 v4, v4, s0
	global_store_short v[2:3], v6, off
	global_store_short v[2:3], v4, off offset:64
	s_waitcnt vmcnt(20)
	v_mul_f32_e32 v2, v14, v233
	v_fma_f32 v2, v30, v232, -v2
	v_mul_f32_e32 v5, v30, v233
	v_mul_f32_e32 v2, 0x3dd53b94, v2
	v_fmac_f32_e32 v5, v14, v232
	v_cvt_pk_bf16_f32 v6, v2, s0
	v_mad_i64_i32 v[2:3], s[0:1], v71, s85, v[66:67]
	v_mul_f32_e32 v4, 0x3dd53b94, v5
	s_nop 0
	v_cvt_pk_bf16_f32 v4, v4, s0
	global_store_short v[2:3], v6, off
	global_store_short v[2:3], v4, off offset:64
	s_waitcnt vmcnt(18)
	v_mul_f32_e32 v2, v15, v235
	v_fma_f32 v2, v31, v234, -v2
	v_mul_f32_e32 v5, v31, v235
	v_mul_f32_e32 v2, 0x3dd53b94, v2
	v_fmac_f32_e32 v5, v15, v234
	v_cvt_pk_bf16_f32 v6, v2, s0
	v_mad_i64_i32 v[2:3], s[0:1], v70, s85, v[66:67]
	v_mul_f32_e32 v4, 0x3dd53b94, v5
	s_nop 0
	v_cvt_pk_bf16_f32 v4, v4, s0
	global_store_short v[2:3], v6, off
	global_store_short v[2:3], v4, off offset:64
	s_waitcnt vmcnt(16)
	v_mul_f32_e32 v2, v16, v237
	v_fma_f32 v2, v32, v236, -v2
	v_mul_f32_e32 v5, v32, v237
	v_mul_f32_e32 v2, 0x3dd53b94, v2
	v_fmac_f32_e32 v5, v16, v236
	v_cvt_pk_bf16_f32 v6, v2, s0
	v_mad_i64_i32 v[2:3], s[0:1], v68, s85, v[66:67]
	v_mul_f32_e32 v4, 0x3dd53b94, v5
	s_nop 0
	v_cvt_pk_bf16_f32 v4, v4, s0
	global_store_short v[2:3], v6, off
	global_store_short v[2:3], v4, off offset:64
	s_waitcnt vmcnt(14)
	v_mul_f32_e32 v2, v17, v239
	v_fma_f32 v2, v33, v238, -v2
	v_mul_f32_e32 v2, 0x3dd53b94, v2
	v_cvt_pk_bf16_f32 v6, v2, s0
	v_mad_i64_i32 v[2:3], s[0:1], v0, s85, v[66:67]
	v_mul_f32_e32 v0, v33, v239
	v_fmac_f32_e32 v0, v17, v238
	v_mul_f32_e32 v0, 0x3dd53b94, v0
	v_cvt_pk_bf16_f32 v0, v0, s0
	global_store_short v[2:3], v6, off
	global_store_short v[2:3], v0, off offset:64
	s_branch .LBB0_548
